# local seams additionally gated on the 256-WG full-program flag
# speedup vs baseline: 1.0060x; 1.0000x over previous
.LBB0_359:
	s_andn2_saveexec_b64 s[6:7], s[6:7]
	s_cbranch_execz .LBB0_377
	s_mov_b64 s[6:7], exec
	buffer_wbl2 sc1
	v_readlane_b32 s98, v246, 1
	v_readlane_b32 s99, v246, 2
	v_mov_b32_e32 v20, 0x3700
	s_nop 4
	global_load_dwordx4 v[24:27], v20, s[98:99] sc1
	global_load_dwordx4 v[28:31], v20, s[98:99] offset:16 sc1
	global_load_dwordx4 v[32:35], v20, s[98:99] offset:256 sc1
	global_load_dwordx4 v[40:43], v20, s[98:99] offset:272 sc1
	buffer_inv sc1
	s_waitcnt lgkmcnt(0)
	s_waitcnt vmcnt(0)
	v_add_u32_e32 v24, v24, v32
	v_xor_b32_e32 v24, 17, v24
	v_add_u32_e32 v25, v25, v33
	v_xor_b32_e32 v25, 17, v25
	v_add_u32_e32 v26, v26, v34
	v_xor_b32_e32 v26, 17, v26
	v_add_u32_e32 v27, v27, v35
	v_xor_b32_e32 v27, 17, v27
	v_add_u32_e32 v28, v28, v40
	v_xor_b32_e32 v28, 17, v28
	v_add_u32_e32 v29, v29, v41
	v_xor_b32_e32 v29, 17, v29
	v_add_u32_e32 v30, v30, v42
	v_xor_b32_e32 v30, 17, v30
	v_add_u32_e32 v31, v31, v43
	v_xor_b32_e32 v31, 17, v31
	v_or3_b32 v24, v24, v25, v26
	v_or3_b32 v27, v27, v28, v29
	v_or3_b32 v24, v24, v30, v31
	v_or_b32_e32 v24, v24, v27
	v_cmp_eq_u32_e32 vcc, 0, v24
	s_and_b64 vcc, vcc, s[92:93]
	s_cbranch_vccnz .LBB0_376
	v_mbcnt_lo_u32_b32 v1, s6, 0
	v_mbcnt_hi_u32_b32 v1, s7, v1
	v_cmp_eq_u32_e32 vcc, 0, v1
	s_and_saveexec_b64 s[8:9], vcc
	s_cbranch_execz .LBB0_362
	s_bcnt1_i32_b64 s6, s[6:7]
	v_mov_b32_e32 v2, 0x283000
	v_mov_b32_e32 v3, s6
	global_atomic_add v2, v2, v3, s[76:77] offset:1024 sc0

.LBB0_859:
	s_andn2_saveexec_b64 s[8:9], s[8:9]
	s_cbranch_execz .LBB0_877
	s_mov_b64 s[8:9], exec
	buffer_wbl2 sc1
	v_readlane_b32 s98, v246, 1
	v_readlane_b32 s99, v246, 2
	v_mov_b32_e32 v20, 0x3700
	s_nop 4
	global_load_dwordx4 v[24:27], v20, s[98:99] sc1
	global_load_dwordx4 v[28:31], v20, s[98:99] offset:16 sc1
	global_load_dwordx4 v[32:35], v20, s[98:99] offset:256 sc1
	global_load_dwordx4 v[40:43], v20, s[98:99] offset:272 sc1
	buffer_inv sc1
	s_waitcnt lgkmcnt(0)
	s_waitcnt vmcnt(0)
	v_add_u32_e32 v24, v24, v32
	v_xor_b32_e32 v24, 17, v24
	v_add_u32_e32 v25, v25, v33
	v_xor_b32_e32 v25, 17, v25
	v_add_u32_e32 v26, v26, v34
	v_xor_b32_e32 v26, 17, v26
	v_add_u32_e32 v27, v27, v35
	v_xor_b32_e32 v27, 17, v27
	v_add_u32_e32 v28, v28, v40
	v_xor_b32_e32 v28, 17, v28
	v_add_u32_e32 v29, v29, v41
	v_xor_b32_e32 v29, 17, v29
	v_add_u32_e32 v30, v30, v42
	v_xor_b32_e32 v30, 17, v30
	v_add_u32_e32 v31, v31, v43
	v_xor_b32_e32 v31, 17, v31
	v_or3_b32 v24, v24, v25, v26
	v_or3_b32 v27, v27, v28, v29
	v_or3_b32 v24, v24, v30, v31
	v_or_b32_e32 v24, v24, v27
	v_cmp_eq_u32_e32 vcc, 0, v24
	s_and_b64 vcc, vcc, s[92:93]
	s_cbranch_vccnz .LBB0_876
	v_mbcnt_lo_u32_b32 v1, s8, 0
	v_mbcnt_hi_u32_b32 v1, s9, v1
	v_cmp_eq_u32_e32 vcc, 0, v1
	s_and_saveexec_b64 s[10:11], vcc
	s_cbranch_execz .LBB0_862
	s_bcnt1_i32_b64 s8, s[8:9]
	v_mov_b32_e32 v2, 0x283000
	v_mov_b32_e32 v3, s8
	global_atomic_add v2, v2, v3, s[76:77] offset:1024 sc0
